# EpiUp rope epilogue de-serialised: 6 of 8 distinct cos/sin table rows loaded once at the start of the rope path, 12 of 16 per-block load+wait pairs removed (on v43)
# speedup vs baseline: 1.0120x; 1.0120x over previous
.LBB0_798:
	v_lshlrev_b32_e32 v248, 4, v177
	v_and_b32_e32 v248, 0x7cf0, v248
	v_or_b32_e32 v248, v248, v172
	v_lshlrev_b32_e32 v248, 2, v248
	global_load_dwordx4 v[190:193], v248, s[48:49]
	global_load_dwordx4 v[194:197], v248, s[46:47]
	v_or_b32_e32 v249, 16, v177
	v_lshlrev_b32_e32 v249, 4, v249
	v_and_b32_e32 v249, 0x7df0, v249
	v_or_b32_e32 v249, v249, v172
	v_lshlrev_b32_e32 v249, 2, v249
	global_load_dwordx4 v[198:201], v249, s[48:49]
	global_load_dwordx4 v[212:215], v249, s[46:47]
	v_or_b32_e32 v248, 32, v177
	v_lshlrev_b32_e32 v248, 4, v248
	v_and_b32_e32 v248, 0x7ef0, v248
	v_or_b32_e32 v248, v248, v172
	v_lshlrev_b32_e32 v248, 2, v248
	global_load_dwordx4 v[216:219], v248, s[48:49]
	global_load_dwordx4 v[220:223], v248, s[46:47]
	v_or_b32_e32 v249, 48, v177
	v_lshlrev_b32_e32 v249, 4, v249
	v_and_b32_e32 v249, 0x7ff0, v249
	v_or_b32_e32 v249, v249, v172
	v_lshlrev_b32_e32 v249, 2, v249
	global_load_dwordx4 v[224:227], v249, s[48:49]
	global_load_dwordx4 v[228:231], v249, s[46:47]
	v_add_u32_e32 v248, 0x80, v177
	v_lshlrev_b32_e32 v248, 4, v248
	v_and_b32_e32 v248, 0x7cf0, v248
	v_or_b32_e32 v248, v248, v172
	v_lshlrev_b32_e32 v248, 2, v248
	global_load_dwordx4 v[232:235], v248, s[48:49]
	global_load_dwordx4 v[236:239], v248, s[46:47]
	v_add_u32_e32 v249, 0x90, v177
	v_lshlrev_b32_e32 v249, 4, v249
	v_and_b32_e32 v249, 0x7df0, v249
	v_or_b32_e32 v249, v249, v172
	v_lshlrev_b32_e32 v249, 2, v249
	global_load_dwordx4 v[240:243], v249, s[48:49]
	global_load_dwordx4 v[244:247], v249, s[46:47]
	v_lshl_add_u64 v[164:165], v[48:49], 2, s[60:61]
	global_load_dword v48, v[164:165], off
	v_lshl_add_u64 v[162:163], v[162:163], 2, s[60:61]
	global_load_dword v162, v[162:163], off
	v_lshl_add_u64 v[160:161], v[160:161], 2, s[60:61]
	global_load_dword v160, v[160:161], off
	v_lshl_add_u64 v[158:159], v[158:159], 2, s[60:61]
	global_load_dword v158, v[158:159], off
	v_lshl_add_u64 v[156:157], v[156:157], 2, s[60:61]
	global_load_dword v156, v[156:157], off
	v_lshl_add_u64 v[152:153], v[152:153], 2, s[60:61]
	global_load_dword v152, v[152:153], off
	v_lshl_add_u64 v[150:151], v[150:151], 2, s[60:61]
	global_load_dword v153, v[150:151], off
	v_lshl_add_u64 v[148:149], v[148:149], 2, s[60:61]
	global_load_dword v178, v[148:149], off
	s_mov_b32 s6, 0x3b800000
	s_waitcnt vmcnt(0)
	s_waitcnt lgkmcnt(0)
	v_mov_b32_e32 v148, v48
	s_nop 1
	v_permlane16_swap_b32_e32 v48, v148
	v_add_f32_e32 v149, v48, v148
	v_mov_b32_e32 v151, v149
	s_nop 1
	v_permlane32_swap_b32_e32 v149, v151
	s_waitcnt lgkmcnt(0)
	v_mov_b32_e32 v48, v162
	s_nop 1
	v_permlane16_swap_b32_e32 v162, v48
	v_add_f32_e32 v148, v162, v48
	v_mov_b32_e32 v150, v148
	s_nop 1
	v_permlane32_swap_b32_e32 v148, v150
	v_pk_add_f32 v[148:149], v[148:149], v[150:151]
	s_nop 0
	v_pk_fma_f32 v[164:165], v[148:149], s[6:7], v[154:155] op_sel_hi:[1,0,0]
	s_mov_b32 s6, 0x55555556
	v_mul_f32_e32 v48, 0x4b800000, v165
	v_cmp_gt_f32_e32 vcc, s75, v165
	v_cmp_gt_f32_e64 s[42:43], s75, v164
	s_nop 0
	v_cndmask_b32_e32 v48, v165, v48, vcc
	v_rsq_f32_e32 v48, v48
	v_lshl_or_b32 v165, v166, 3, s88
	v_mul_f32_e32 v148, 0x45800000, v48
	v_cndmask_b32_e32 v48, v48, v148, vcc
	v_mul_f32_e32 v148, 0x3e16c740, v48
	s_waitcnt lgkmcnt(0)
	v_mov_b32_e32 v48, v160
	s_nop 1
	v_permlane16_swap_b32_e32 v160, v48
	v_add_f32_e32 v161, v160, v48
	v_mov_b32_e32 v163, v161
	s_nop 1
	v_permlane32_swap_b32_e32 v161, v163
	s_waitcnt lgkmcnt(0)
	v_mov_b32_e32 v48, v158
	s_nop 1
	v_permlane16_swap_b32_e32 v158, v48
	v_add_f32_e32 v160, v158, v48
	v_mov_b32_e32 v162, v160
	s_nop 1
	v_permlane32_swap_b32_e32 v160, v162
	s_waitcnt lgkmcnt(0)
	v_mov_b32_e32 v48, v156
	s_nop 1
	v_permlane16_swap_b32_e32 v156, v48
	v_add_f32_e32 v157, v156, v48
	v_mov_b32_e32 v159, v157
	s_nop 1
	v_permlane32_swap_b32_e32 v157, v159
	s_waitcnt lgkmcnt(0)
	v_mov_b32_e32 v48, v152
	s_nop 1
	v_permlane16_swap_b32_e32 v152, v48
	v_add_f32_e32 v156, v152, v48
	v_mov_b32_e32 v158, v156
	s_nop 1
	v_permlane32_swap_b32_e32 v156, v158
	s_waitcnt lgkmcnt(0)
	v_mov_b32_e32 v48, v153
	s_nop 1
	v_permlane16_swap_b32_e32 v153, v48
	v_add_f32_e32 v151, v153, v48
	ds_bpermute_b32 v48, v167, v178
	v_mov_b32_e32 v153, v151
	s_nop 1
	v_permlane32_swap_b32_e32 v151, v153
	s_waitcnt lgkmcnt(0)
	v_add_f32_e32 v150, v178, v48
	v_mul_hi_i32 v48, v165, s6
	v_lshrrev_b32_e32 v149, 31, v48
	v_add_u32_e32 v48, v48, v149
	v_lshl_add_u32 v48, v48, 1, v48
	v_sub_u32_e32 v48, v165, v48
	v_mov_b32_e32 v152, v150
	v_cmp_eq_u32_e32 vcc, 2, v48
	v_lshlrev_b32_e32 v48, 4, v177
	s_movk_i32 s6, 0x7cf0
	v_permlane32_swap_b32_e32 v150, v152
	v_pk_mul_f32 v[128:129], v[128:129], v[148:149] op_sel_hi:[1,0]
	v_pk_mul_f32 v[126:127], v[126:127], v[148:149] op_sel_hi:[1,0]
	v_pk_mul_f32 v[124:125], v[124:125], v[148:149] op_sel_hi:[1,0]
	v_pk_mul_f32 v[166:167], v[122:123], v[148:149] op_sel_hi:[1,0]
	v_and_or_b32 v123, v48, s6, v172
	s_and_saveexec_b64 s[44:45], vcc
	s_cbranch_execz .LBB0_800
	v_lshlrev_b32_e32 v48, 2, v123
	v_pk_mul_f32 v[186:187], v[124:125], v[192:193]
	v_pk_mul_f32 v[188:189], v[166:167], v[190:191]
	v_pk_mul_f32 v[180:181], v[128:129], v[192:193]
	v_pk_mul_f32 v[178:179], v[126:127], v[190:191]
	v_pk_fma_f32 v[128:129], v[128:129], v[196:197], v[186:187] neg_lo:[0,0,1] neg_hi:[0,0,1]
	v_pk_fma_f32 v[126:127], v[126:127], v[194:195], v[188:189] neg_lo:[0,0,1] neg_hi:[0,0,1]
	v_pk_fma_f32 v[124:125], v[124:125], v[196:197], v[180:181]
	v_pk_fma_f32 v[166:167], v[166:167], v[194:195], v[178:179]
.LBB0_800:
	s_or_b64 exec, exec, s[44:45]
	v_mul_f32_e32 v48, 0x4b800000, v164
	v_cndmask_b32_e64 v48, v164, v48, s[42:43]
	v_rsq_f32_e32 v48, v48
	v_lshl_or_b32 v164, v165, 5, v169
	v_cvt_pk_bf16_f32 v179, v128, v129
	v_mul_lo_u32 v128, v177, s95
	v_mul_f32_e32 v122, 0x45800000, v48
	v_cndmask_b32_e64 v48, v48, v122, s[42:43]
	v_mul_f32_e32 v122, 0x3e16c740, v48
	v_add_u32_e32 v48, v128, v164
	v_cvt_pk_bf16_f32 v178, v126, v127
	v_cvt_pk_bf16_f32 v180, v166, v167
	v_cvt_pk_bf16_f32 v181, v124, v125
	v_lshl_add_u64 v[124:125], v[48:49], 1, s[56:57]
	global_store_dwordx4 v[124:125], v[178:181], off
	s_nop 1
	v_or_b32_e32 v48, 16, v177
	v_lshlrev_b32_e32 v48, 4, v48
	s_movk_i32 s6, 0x7df0
	v_pk_mul_f32 v[120:121], v[120:121], v[122:123] op_sel_hi:[1,0]
	v_pk_mul_f32 v[118:119], v[118:119], v[122:123] op_sel_hi:[1,0]
	v_pk_mul_f32 v[124:125], v[116:117], v[122:123] op_sel_hi:[1,0]
	v_pk_mul_f32 v[126:127], v[114:115], v[122:123] op_sel_hi:[1,0]
	v_and_or_b32 v115, v48, s6, v172
	s_and_saveexec_b64 s[42:43], vcc
	s_cbranch_execz .LBB0_802
	v_lshlrev_b32_e32 v48, 2, v115
	v_pk_mul_f32 v[116:117], v[124:125], v[200:201]
	v_pk_mul_f32 v[166:167], v[126:127], v[198:199]
	v_pk_mul_f32 v[180:181], v[120:121], v[200:201]
	v_pk_mul_f32 v[178:179], v[118:119], v[198:199]
	v_pk_fma_f32 v[120:121], v[120:121], v[214:215], v[116:117] neg_lo:[0,0,1] neg_hi:[0,0,1]
	v_pk_fma_f32 v[118:119], v[118:119], v[212:213], v[166:167] neg_lo:[0,0,1] neg_hi:[0,0,1]
	v_pk_fma_f32 v[124:125], v[124:125], v[214:215], v[180:181]
	v_pk_fma_f32 v[126:127], v[126:127], v[212:213], v[178:179]
.LBB0_802:
	s_or_b64 exec, exec, s[42:43]
	v_pk_add_f32 v[116:117], v[160:161], v[162:163]
	s_mov_b32 s6, 0x3b800000
	v_pk_fma_f32 v[116:117], v[116:117], s[6:7], v[154:155] op_sel_hi:[1,0,0]
	v_cvt_pk_bf16_f32 v160, v118, v119
	v_mul_f32_e32 v48, 0x4b800000, v117
	v_cmp_gt_f32_e64 s[44:45], s75, v117
	v_add_u32_e32 v118, 0x3000, v128
	v_cvt_pk_bf16_f32 v161, v120, v121
	v_cndmask_b32_e64 v48, v117, v48, s[44:45]
	v_rsq_f32_e32 v48, v48
	v_cvt_pk_bf16_f32 v162, v126, v127
	v_cvt_pk_bf16_f32 v163, v124, v125
	s_movk_i32 s6, 0x7ef0
	v_mul_f32_e32 v114, 0x45800000, v48
	v_cndmask_b32_e64 v48, v48, v114, s[44:45]
	v_mul_f32_e32 v114, 0x3e16c740, v48
	v_add_u32_e32 v48, v118, v164
	v_lshl_add_u64 v[120:121], v[48:49], 1, s[56:57]
	global_store_dwordx4 v[120:121], v[160:163], off
	s_nop 1
	v_or_b32_e32 v48, 32, v177
	v_lshlrev_b32_e32 v48, 4, v48
	v_cmp_gt_f32_e64 s[42:43], s75, v116
	v_pk_mul_f32 v[112:113], v[112:113], v[114:115] op_sel_hi:[1,0]
	v_pk_mul_f32 v[110:111], v[110:111], v[114:115] op_sel_hi:[1,0]
	v_pk_mul_f32 v[108:109], v[108:109], v[114:115] op_sel_hi:[1,0]
	v_pk_mul_f32 v[106:107], v[106:107], v[114:115] op_sel_hi:[1,0]
	v_and_or_b32 v117, v48, s6, v172
	s_and_saveexec_b64 s[44:45], vcc
	s_cbranch_execz .LBB0_804
	v_lshlrev_b32_e32 v48, 2, v117
	v_pk_mul_f32 v[120:121], v[108:109], v[218:219]
	v_pk_mul_f32 v[166:167], v[106:107], v[216:217]
	v_pk_mul_f32 v[126:127], v[112:113], v[218:219]
	v_pk_mul_f32 v[124:125], v[110:111], v[216:217]
	v_pk_fma_f32 v[112:113], v[112:113], v[222:223], v[120:121] neg_lo:[0,0,1] neg_hi:[0,0,1]
	v_pk_fma_f32 v[110:111], v[110:111], v[220:221], v[166:167] neg_lo:[0,0,1] neg_hi:[0,0,1]
	v_pk_fma_f32 v[108:109], v[108:109], v[222:223], v[126:127]
	v_pk_fma_f32 v[106:107], v[106:107], v[220:221], v[124:125]
.LBB0_804:
	s_or_b64 exec, exec, s[44:45]
	v_mul_f32_e32 v48, 0x4b800000, v116
	v_cndmask_b32_e64 v48, v116, v48, s[42:43]
	v_rsq_f32_e32 v48, v48
	v_cvt_pk_bf16_f32 v126, v106, v107
	v_cvt_pk_bf16_f32 v125, v112, v113
	v_add_u32_e32 v112, 0x3000, v118
	v_mul_f32_e32 v106, 0x45800000, v48
	v_cndmask_b32_e64 v48, v48, v106, s[42:43]
	v_mul_f32_e32 v106, 0x3e16c740, v48
	v_add_u32_e32 v48, v112, v164
	v_cvt_pk_bf16_f32 v124, v110, v111
	v_cvt_pk_bf16_f32 v127, v108, v109
	v_lshl_add_u64 v[108:109], v[48:49], 1, s[56:57]
	global_store_dwordx4 v[108:109], v[124:127], off
	s_nop 1
	v_or_b32_e32 v48, 48, v177
	v_lshlrev_b32_e32 v48, 4, v48
	s_movk_i32 s6, 0x7ff0
	v_pk_mul_f32 v[104:105], v[104:105], v[106:107] op_sel_hi:[1,0]
	v_pk_mul_f32 v[102:103], v[102:103], v[106:107] op_sel_hi:[1,0]
	v_pk_mul_f32 v[108:109], v[100:101], v[106:107] op_sel_hi:[1,0]
	v_pk_mul_f32 v[110:111], v[98:99], v[106:107] op_sel_hi:[1,0]
	v_and_or_b32 v99, v48, s6, v172
	s_and_saveexec_b64 s[42:43], vcc
	s_cbranch_execz .LBB0_806
	v_lshlrev_b32_e32 v48, 2, v99
	v_pk_mul_f32 v[100:101], v[108:109], v[226:227]
	v_pk_mul_f32 v[120:121], v[110:111], v[224:225]
	v_pk_mul_f32 v[126:127], v[104:105], v[226:227]
	v_pk_mul_f32 v[124:125], v[102:103], v[224:225]
	v_pk_fma_f32 v[104:105], v[104:105], v[230:231], v[100:101] neg_lo:[0,0,1] neg_hi:[0,0,1]
	v_pk_fma_f32 v[102:103], v[102:103], v[228:229], v[120:121] neg_lo:[0,0,1] neg_hi:[0,0,1]
	v_pk_fma_f32 v[108:109], v[108:109], v[230:231], v[126:127]
	v_pk_fma_f32 v[110:111], v[110:111], v[228:229], v[124:125]
.LBB0_806:
	s_or_b64 exec, exec, s[42:43]
	v_pk_add_f32 v[100:101], v[156:157], v[158:159]
	s_mov_b32 s6, 0x3b800000
	v_pk_fma_f32 v[100:101], v[100:101], s[6:7], v[154:155] op_sel_hi:[1,0,0]
	v_cvt_pk_bf16_f32 v124, v102, v103
	v_mul_f32_e32 v48, 0x4b800000, v101
	v_cmp_gt_f32_e64 s[44:45], s75, v101
	v_add_u32_e32 v102, 0x3000, v112
	v_cvt_pk_bf16_f32 v125, v104, v105
	v_cndmask_b32_e64 v48, v101, v48, s[44:45]
	v_rsq_f32_e32 v48, v48
	v_cvt_pk_bf16_f32 v126, v110, v111
	v_cvt_pk_bf16_f32 v127, v108, v109
	s_movk_i32 s6, 0x7cf0
	v_mul_f32_e32 v98, 0x45800000, v48
	v_cndmask_b32_e64 v48, v48, v98, s[44:45]
	v_mul_f32_e32 v98, 0x3e16c740, v48
	v_add_u32_e32 v48, v102, v164
	v_lshl_add_u64 v[104:105], v[48:49], 1, s[56:57]
	global_store_dwordx4 v[104:105], v[124:127], off
	s_nop 1
	v_add_u32_e32 v48, 0x80, v177
	v_lshlrev_b32_e32 v48, 4, v48
	v_cmp_gt_f32_e64 s[42:43], s75, v100
	v_pk_mul_f32 v[96:97], v[96:97], v[98:99] op_sel_hi:[1,0]
	v_pk_mul_f32 v[94:95], v[94:95], v[98:99] op_sel_hi:[1,0]
	v_pk_mul_f32 v[92:93], v[92:93], v[98:99] op_sel_hi:[1,0]
	v_pk_mul_f32 v[90:91], v[90:91], v[98:99] op_sel_hi:[1,0]
	v_and_or_b32 v101, v48, s6, v172
	s_and_saveexec_b64 s[44:45], vcc
	s_cbranch_execz .LBB0_808
	v_lshlrev_b32_e32 v48, 2, v101
	v_pk_mul_f32 v[104:105], v[92:93], v[234:235]
	v_pk_mul_f32 v[120:121], v[90:91], v[232:233]
	v_pk_mul_f32 v[110:111], v[96:97], v[234:235]
	v_pk_mul_f32 v[108:109], v[94:95], v[232:233]
	v_pk_fma_f32 v[96:97], v[96:97], v[238:239], v[104:105] neg_lo:[0,0,1] neg_hi:[0,0,1]
	v_pk_fma_f32 v[94:95], v[94:95], v[236:237], v[120:121] neg_lo:[0,0,1] neg_hi:[0,0,1]
	v_pk_fma_f32 v[92:93], v[92:93], v[238:239], v[110:111]
	v_pk_fma_f32 v[90:91], v[90:91], v[236:237], v[108:109]
.LBB0_808:
	s_or_b64 exec, exec, s[44:45]
	v_mul_f32_e32 v48, 0x4b800000, v100
	v_cndmask_b32_e64 v48, v100, v48, s[42:43]
	v_rsq_f32_e32 v48, v48
	v_cvt_pk_bf16_f32 v110, v90, v91
	v_cvt_pk_bf16_f32 v109, v96, v97
	v_add_u32_e32 v96, 0xf000, v102
	v_mul_f32_e32 v90, 0x45800000, v48
	v_cndmask_b32_e64 v48, v48, v90, s[42:43]
	v_mul_f32_e32 v90, 0x3e16c740, v48
	v_add_u32_e32 v48, v96, v164
	v_cvt_pk_bf16_f32 v108, v94, v95
	v_cvt_pk_bf16_f32 v111, v92, v93
	v_lshl_add_u64 v[92:93], v[48:49], 1, s[56:57]
	global_store_dwordx4 v[92:93], v[108:111], off
	s_nop 1
	v_add_u32_e32 v48, 0x90, v177
	v_lshlrev_b32_e32 v48, 4, v48
	s_movk_i32 s6, 0x7df0
	v_pk_mul_f32 v[88:89], v[88:89], v[90:91] op_sel_hi:[1,0]
	v_pk_mul_f32 v[86:87], v[86:87], v[90:91] op_sel_hi:[1,0]
	v_pk_mul_f32 v[92:93], v[84:85], v[90:91] op_sel_hi:[1,0]
	v_pk_mul_f32 v[94:95], v[82:83], v[90:91] op_sel_hi:[1,0]
	v_and_or_b32 v83, v48, s6, v172
	s_and_saveexec_b64 s[42:43], vcc
	s_cbranch_execz .LBB0_810
	v_lshlrev_b32_e32 v48, 2, v83
	v_pk_mul_f32 v[84:85], v[92:93], v[242:243]
	v_pk_mul_f32 v[104:105], v[94:95], v[240:241]
	v_pk_mul_f32 v[110:111], v[88:89], v[242:243]
	v_pk_mul_f32 v[108:109], v[86:87], v[240:241]
	v_pk_fma_f32 v[88:89], v[88:89], v[246:247], v[84:85] neg_lo:[0,0,1] neg_hi:[0,0,1]
	v_pk_fma_f32 v[86:87], v[86:87], v[244:245], v[104:105] neg_lo:[0,0,1] neg_hi:[0,0,1]
	v_pk_fma_f32 v[92:93], v[92:93], v[246:247], v[110:111]
	v_pk_fma_f32 v[94:95], v[94:95], v[244:245], v[108:109]

.LBB0_814:
	s_or_b64 exec, exec, s[42:43]
	v_cvt_pk_bf16_f32 v70, v70, v71
	v_cvt_pk_bf16_f32 v71, v72, v73
	v_cvt_pk_bf16_f32 v72, v66, v67
	v_add_u32_e32 v66, 0x3000, v77
	v_add_u32_e32 v48, v66, v164
	v_cvt_pk_bf16_f32 v73, v68, v69
	v_lshl_add_u64 v[68:69], v[48:49], 1, s[56:57]
	v_or_b32_e32 v48, 4, v165
	s_mov_b32 s6, 0x55555556
	v_mul_hi_i32 v67, v48, s6
	global_store_dwordx4 v[68:69], v[70:73], off
	s_nop 1
	v_lshrrev_b32_e32 v68, 31, v67
	v_add_u32_e32 v67, v67, v68
	v_lshl_add_u32 v67, v67, 1, v67
	v_mov_b32_e32 v149, v148
	v_sub_u32_e32 v67, v48, v67
	v_mov_b32_e32 v68, v148
	v_mov_b32_e32 v69, v148
	v_cmp_eq_u32_e32 vcc, 2, v67
	v_pk_mul_f32 v[64:65], v[64:65], v[68:69]
	v_pk_mul_f32 v[62:63], v[62:63], v[148:149]
	v_pk_mul_f32 v[60:61], v[60:61], v[68:69]
	v_pk_mul_f32 v[58:59], v[58:59], v[148:149]
	s_and_saveexec_b64 s[42:43], vcc
	s_cbranch_execz .LBB0_816
	v_lshlrev_b32_e32 v67, 2, v123
	v_pk_mul_f32 v[72:73], v[60:61], v[192:193]
	v_pk_mul_f32 v[88:89], v[58:59], v[190:191]
	v_pk_mul_f32 v[70:71], v[64:65], v[192:193]
	v_pk_mul_f32 v[68:69], v[62:63], v[190:191]
	v_pk_fma_f32 v[64:65], v[64:65], v[196:197], v[72:73] neg_lo:[0,0,1] neg_hi:[0,0,1]
	v_pk_fma_f32 v[62:63], v[62:63], v[194:195], v[88:89] neg_lo:[0,0,1] neg_hi:[0,0,1]
	v_pk_fma_f32 v[60:61], v[60:61], v[196:197], v[70:71]
	v_pk_fma_f32 v[58:59], v[58:59], v[194:195], v[68:69]
.LBB0_816:
	s_or_b64 exec, exec, s[42:43]
	v_lshl_or_b32 v67, v48, 5, v169
	v_add_u32_e32 v48, v67, v128
	v_cvt_pk_bf16_f32 v62, v62, v63
	v_cvt_pk_bf16_f32 v63, v64, v65
	v_cvt_pk_bf16_f32 v64, v58, v59
	v_cvt_pk_bf16_f32 v65, v60, v61
	v_lshl_add_u64 v[58:59], v[48:49], 1, s[56:57]
	global_store_dwordx4 v[58:59], v[62:65], off
	s_nop 1
	v_mov_b32_e32 v123, v122
	v_mov_b32_e32 v58, v122
	v_mov_b32_e32 v59, v122
	v_pk_mul_f32 v[56:57], v[56:57], v[58:59]
	v_pk_mul_f32 v[54:55], v[54:55], v[122:123]
	v_pk_mul_f32 v[52:53], v[52:53], v[58:59]
	v_pk_mul_f32 v[50:51], v[50:51], v[122:123]
	s_and_saveexec_b64 s[42:43], vcc
	s_cbranch_execz .LBB0_818
	v_lshlrev_b32_e32 v48, 2, v115
	v_pk_mul_f32 v[68:69], v[52:53], v[200:201]
	v_pk_mul_f32 v[70:71], v[50:51], v[198:199]
	v_pk_mul_f32 v[60:61], v[56:57], v[200:201]
	v_pk_mul_f32 v[58:59], v[54:55], v[198:199]
	v_pk_fma_f32 v[56:57], v[56:57], v[214:215], v[68:69] neg_lo:[0,0,1] neg_hi:[0,0,1]
	v_pk_fma_f32 v[54:55], v[54:55], v[212:213], v[70:71] neg_lo:[0,0,1] neg_hi:[0,0,1]
	v_pk_fma_f32 v[52:53], v[52:53], v[214:215], v[60:61]
	v_pk_fma_f32 v[50:51], v[50:51], v[212:213], v[58:59]
.LBB0_818:
	s_or_b64 exec, exec, s[42:43]
	v_add_u32_e32 v48, v118, v67
	v_cvt_pk_bf16_f32 v54, v54, v55
	v_cvt_pk_bf16_f32 v55, v56, v57
	v_cvt_pk_bf16_f32 v56, v50, v51
	v_cvt_pk_bf16_f32 v57, v52, v53
	v_lshl_add_u64 v[50:51], v[48:49], 1, s[56:57]
	global_store_dwordx4 v[50:51], v[54:57], off
	s_nop 1
	v_mov_b32_e32 v115, v114
	v_mov_b32_e32 v50, v114
	v_mov_b32_e32 v51, v114
	v_pk_mul_f32 v[46:47], v[46:47], v[50:51]
	v_pk_mul_f32 v[44:45], v[44:45], v[114:115]
	v_pk_mul_f32 v[42:43], v[42:43], v[50:51]
	v_pk_mul_f32 v[40:41], v[40:41], v[114:115]
	s_and_saveexec_b64 s[42:43], vcc
	s_cbranch_execz .LBB0_820
	v_lshlrev_b32_e32 v48, 2, v117
	v_pk_mul_f32 v[58:59], v[42:43], v[218:219]
	v_pk_mul_f32 v[60:61], v[40:41], v[216:217]
	v_pk_mul_f32 v[52:53], v[46:47], v[218:219]
	v_pk_mul_f32 v[50:51], v[44:45], v[216:217]
	v_pk_fma_f32 v[46:47], v[46:47], v[222:223], v[58:59] neg_lo:[0,0,1] neg_hi:[0,0,1]
	v_pk_fma_f32 v[44:45], v[44:45], v[220:221], v[60:61] neg_lo:[0,0,1] neg_hi:[0,0,1]
	v_pk_fma_f32 v[42:43], v[42:43], v[222:223], v[52:53]
	v_pk_fma_f32 v[40:41], v[40:41], v[220:221], v[50:51]
.LBB0_820:
	s_or_b64 exec, exec, s[42:43]
	v_add_u32_e32 v48, v112, v67
	v_cvt_pk_bf16_f32 v44, v44, v45
	v_cvt_pk_bf16_f32 v45, v46, v47
	v_cvt_pk_bf16_f32 v46, v40, v41
	v_cvt_pk_bf16_f32 v47, v42, v43
	v_lshl_add_u64 v[40:41], v[48:49], 1, s[56:57]
	global_store_dwordx4 v[40:41], v[44:47], off
	s_nop 1
	v_mov_b32_e32 v107, v106
	v_mov_b32_e32 v40, v106
	v_mov_b32_e32 v41, v106
	v_pk_mul_f32 v[38:39], v[38:39], v[40:41]
	v_pk_mul_f32 v[36:37], v[36:37], v[106:107]
	v_pk_mul_f32 v[34:35], v[34:35], v[40:41]
	v_pk_mul_f32 v[32:33], v[32:33], v[106:107]
	s_and_saveexec_b64 s[42:43], vcc
	s_cbranch_execz .LBB0_822
	v_lshlrev_b32_e32 v44, 2, v99
	v_pk_mul_f32 v[50:51], v[34:35], v[226:227]
	v_pk_mul_f32 v[52:53], v[32:33], v[224:225]
	v_pk_mul_f32 v[42:43], v[38:39], v[226:227]
	v_pk_mul_f32 v[40:41], v[36:37], v[224:225]
	v_pk_fma_f32 v[38:39], v[38:39], v[230:231], v[50:51] neg_lo:[0,0,1] neg_hi:[0,0,1]
	v_pk_fma_f32 v[36:37], v[36:37], v[228:229], v[52:53] neg_lo:[0,0,1] neg_hi:[0,0,1]
	v_pk_fma_f32 v[34:35], v[34:35], v[230:231], v[42:43]
	v_pk_fma_f32 v[32:33], v[32:33], v[228:229], v[40:41]
.LBB0_822:
	s_or_b64 exec, exec, s[42:43]
	v_add_u32_e32 v48, v102, v67
	v_cvt_pk_bf16_f32 v36, v36, v37
	v_cvt_pk_bf16_f32 v37, v38, v39
	v_cvt_pk_bf16_f32 v38, v32, v33
	v_cvt_pk_bf16_f32 v39, v34, v35
	v_lshl_add_u64 v[32:33], v[48:49], 1, s[56:57]
	global_store_dwordx4 v[32:33], v[36:39], off
	s_nop 1
	v_mov_b32_e32 v99, v98
	v_mov_b32_e32 v32, v98
	v_mov_b32_e32 v33, v98
	v_pk_mul_f32 v[30:31], v[30:31], v[32:33]
	v_pk_mul_f32 v[28:29], v[28:29], v[98:99]
	v_pk_mul_f32 v[26:27], v[26:27], v[32:33]
	v_pk_mul_f32 v[24:25], v[24:25], v[98:99]
	s_and_saveexec_b64 s[42:43], vcc
	s_cbranch_execz .LBB0_824
	v_lshlrev_b32_e32 v36, 2, v101
	v_pk_mul_f32 v[40:41], v[26:27], v[234:235]
	v_pk_mul_f32 v[42:43], v[24:25], v[232:233]
	v_pk_mul_f32 v[34:35], v[30:31], v[234:235]
	v_pk_mul_f32 v[32:33], v[28:29], v[232:233]
	v_pk_fma_f32 v[30:31], v[30:31], v[238:239], v[40:41] neg_lo:[0,0,1] neg_hi:[0,0,1]
	v_pk_fma_f32 v[28:29], v[28:29], v[236:237], v[42:43] neg_lo:[0,0,1] neg_hi:[0,0,1]
	v_pk_fma_f32 v[26:27], v[26:27], v[238:239], v[34:35]
	v_pk_fma_f32 v[24:25], v[24:25], v[236:237], v[32:33]
.LBB0_824:
	s_or_b64 exec, exec, s[42:43]
	v_add_u32_e32 v48, v96, v67
	v_cvt_pk_bf16_f32 v28, v28, v29
	v_cvt_pk_bf16_f32 v29, v30, v31
	v_cvt_pk_bf16_f32 v30, v24, v25
	v_cvt_pk_bf16_f32 v31, v26, v27
	v_lshl_add_u64 v[24:25], v[48:49], 1, s[56:57]
	global_store_dwordx4 v[24:25], v[28:31], off
	s_nop 1
	v_mov_b32_e32 v91, v90
	v_mov_b32_e32 v24, v90
	v_mov_b32_e32 v25, v90
	v_pk_mul_f32 v[22:23], v[22:23], v[24:25]
	v_pk_mul_f32 v[20:21], v[20:21], v[90:91]
	v_pk_mul_f32 v[18:19], v[18:19], v[24:25]
	v_pk_mul_f32 v[16:17], v[16:17], v[90:91]
	s_and_saveexec_b64 s[42:43], vcc
	s_cbranch_execz .LBB0_826
	v_lshlrev_b32_e32 v28, 2, v83
	v_pk_mul_f32 v[32:33], v[18:19], v[242:243]
	v_pk_mul_f32 v[34:35], v[16:17], v[240:241]
	v_pk_mul_f32 v[26:27], v[22:23], v[242:243]
	v_pk_mul_f32 v[24:25], v[20:21], v[240:241]
	v_pk_fma_f32 v[22:23], v[22:23], v[246:247], v[32:33] neg_lo:[0,0,1] neg_hi:[0,0,1]
	v_pk_fma_f32 v[20:21], v[20:21], v[244:245], v[34:35] neg_lo:[0,0,1] neg_hi:[0,0,1]
	v_pk_fma_f32 v[18:19], v[18:19], v[246:247], v[26:27]
	v_pk_fma_f32 v[16:17], v[16:17], v[244:245], v[24:25]
